# SSD phase: odd workgroups run the bandwidth-bound sample units before their latency-bound prompt unit (de-synchronises the HBM burst)
# speedup vs baseline: 1.0216x; 1.0216x over previous
.LBB0_831:
.LBB0_832:
	s_mov_b32 s98, 0
	s_cmp_lt_i32 s50, 4
	s_cselect_b64 s[0:1], -1, 0
	s_and_b64 s[56:57], s[0:1], s[4:5]
	s_andn2_b64 vcc, exec, s[56:57]
	s_cbranch_vccnz .LBB0_922
	s_mov_b64 s[96:97], s[84:85]
	s_cmpk_gt_i32 s2, 0xff
	s_cbranch_scc1 .LBB0_886
	s_bitcmp1_b32 s2, 0
	s_cbranch_scc0 .Lssd_prompt
	s_mov_b32 s98, 1
	s_branch .LBB0_886
.Lssd_prompt:
	s_add_u32 s58, s46, 0x5200000
	s_addc_u32 s59, s47, 0
	s_add_u32 s60, s46, 0x3000000
	s_addc_u32 s61, s47, 0
	s_add_u32 s62, s46, 0x1bb00000
	s_waitcnt vmcnt(0)
	v_lshrrev_b32_e32 v60, 4, v178
	v_lshlrev_b32_e32 v4, 3, v178
	s_addc_u32 s63, s47, 0
	v_and_b32_e32 v2, 56, v4
	v_and_b32_e32 v4, 0x78, v4
	v_mul_u32_u24_e32 v8, 0x88, v60
	v_and_b32_e32 v1, 63, v178
	s_add_u32 s64, s46, 0x1af00000
	v_lshlrev_b32_e32 v8, 1, v8
	v_lshlrev_b32_e32 v9, 1, v4
	s_addc_u32 s65, s47, 0
	v_add3_u32 v61, 0, v8, v9
	s_add_i32 s33, 0, 0x1a400
	v_lshlrev_b32_e32 v9, 2, v1
	s_add_i32 s34, 0, 0x1a500
	v_lshrrev_b32_e32 v58, 3, v178
	v_add_u32_e32 v65, s33, v9
	v_add_u32_e32 v85, s34, v9
	v_and_b32_e32 v9, 0x7f, v178
	v_lshrrev_b32_e32 v10, 7, v178
	v_cmp_eq_u32_e64 s[8:9], 0, v1
	v_cmp_gt_u32_e64 s[10:11], 2, v1
	v_cmp_gt_u32_e64 s[12:13], 4, v1
	v_cmp_gt_u32_e64 s[14:15], 8, v1
	v_cmp_gt_u32_e64 s[16:17], 16, v1
	v_cmp_gt_u32_e64 s[18:19], 32, v1
	v_mul_u32_u24_e32 v1, 0x48, v2
	v_bfe_u32 v3, v178, 4, 2
	v_lshlrev_b32_e32 v6, 1, v58
	s_add_i32 s0, 0, 0x11400
	v_lshlrev_b32_e32 v11, 4, v10
	v_lshl_add_u32 v13, v9, 1, 0
	v_mul_u32_u24_e32 v9, 0x8e, v9
	v_lshlrev_b32_e32 v12, 5, v10
	v_lshlrev_b32_e32 v1, 1, v1
	v_and_b32_e32 v5, 15, v178
	v_add3_u32 v106, v13, v9, v12
	v_lshlrev_b32_e32 v12, 2, v3
	v_and_b32_e32 v15, 48, v178
	v_add3_u32 v113, s0, v6, v1
	v_add3_u32 v114, s0, v1, v6
	v_lshlrev_b32_e32 v1, 6, v10
	v_or_b32_e32 v6, 1, v11
	v_lshrrev_b32_e32 v9, 5, v178
	v_or_b32_e32 v107, v12, v11
	v_or_b32_e32 v14, v11, v5
	v_add_u32_e32 v17, 0, v15
	s_movk_i32 s6, 0x110
	v_mul_u32_u24_e32 v11, 0x110, v6
	v_or_b32_e32 v6, 16, v1
	v_mul_u32_u24_e32 v7, 0x48, v58
	v_and_b32_e32 v9, 2, v9
	v_mad_u32_u24 v108, v14, s6, v17
	v_mul_u32_u24_e32 v14, 0x90, v14
	s_add_i32 s43, 0, 0x13800
	v_add_u32_e32 v118, s34, v1
	v_add_u32_e32 v119, s33, v1
	v_add_u32_e32 v120, s34, v6
	v_add_u32_e32 v121, s33, v6
	v_or_b32_e32 v6, 32, v1
	v_or_b32_e32 v1, 48, v1
	s_add_i32 s3, 0, 0x15c00
	v_lshlrev_b32_e32 v7, 1, v7
	v_lshlrev_b32_e32 v62, 1, v2
	v_lshlrev_b32_e32 v8, 1, v5
	v_add3_u32 v109, s43, v14, v15
	v_add_u32_e32 v110, s0, v15
	v_lshlrev_b32_e32 v15, 5, v179
	s_add_i32 s52, 0, 0x18000
	v_add_u32_e32 v124, s34, v1
	v_add_u32_e32 v125, s33, v1
	v_lshl_or_b32 v1, v9, 4, v5
	s_movk_i32 s1, 0x48
	v_add3_u32 v59, s3, v7, v62
	s_movk_i32 s42, 0x90
	v_add3_u32 v15, 0, v8, v15
	v_add3_u32 v112, s52, v7, v62
	v_mul_u32_u24_e32 v7, 0x1100, v10
	v_cmp_le_u32_e64 s[20:21], v9, v10
	v_or_b32_e32 v8, 2, v107
	v_mov_b32_e32 v18, 0x1b0
	v_cmp_lt_u32_e64 s[22:23], v9, v10
	v_or_b32_e32 v9, 16, v1
	v_mul_u32_u24_e32 v10, 0x48, v107
	v_lshl_add_u32 v130, v8, 2, s33
	v_mad_u32_u24 v133, v107, s42, v18
	v_mad_u32_u24 v18, v107, s1, s1
	v_mov_b32_e32 v20, 0x90
	v_cmp_le_u32_e64 s[28:29], v1, v8
	v_cmp_le_u32_e64 s[38:39], v9, v8
	v_add_lshl_u32 v8, v10, v1, 1
	v_mad_u32_u24 v20, v107, s1, v20
	v_mov_b32_e32 v21, 0xd8
	v_add_u32_e32 v145, s3, v8
	v_add_u32_e32 v146, s52, v8
	v_add_lshl_u32 v8, v18, v1, 1
	v_mad_u32_u24 v21, v107, s1, v21
	v_add_u32_e32 v147, s3, v8
	v_add_u32_e32 v148, s52, v8
	v_add_lshl_u32 v8, v20, v1, 1
	v_mov_b32_e32 v16, 0x120
	v_add_u32_e32 v149, s3, v8
	v_add_u32_e32 v150, s52, v8
	v_add_lshl_u32 v8, v21, v1, 1
	v_add_u32_e32 v122, s34, v6
	v_add_u32_e32 v123, s33, v6
	v_or_b32_e32 v6, 1, v107
	v_mad_u32_u24 v131, v107, s42, v16
	v_or_b32_e32 v16, 3, v107
	v_add_u32_e32 v151, s3, v8
	v_add_u32_e32 v152, s52, v8
	v_mov_b32_e32 v8, 0x900
	v_mul_u32_u24_e32 v19, 0x110, v1
	v_lshlrev_b32_e32 v22, 2, v1
	v_lshl_add_u32 v136, v1, 1, s43
	v_cmp_le_u32_e64 s[24:25], v1, v107
	v_cmp_le_u32_e64 s[26:27], v1, v6
	v_cmp_le_u32_e64 s[30:31], v1, v16
	v_mul_u32_u24_e32 v143, 0x90, v1
	v_mad_u32_u24 v153, v1, s42, v8
	v_add_lshl_u32 v1, v9, v10, 1
	v_lshl_or_b32 v14, v179, 4, v5
	v_lshl_add_u32 v128, v6, 2, s33
	v_cmp_le_u32_e64 s[36:37], v9, v6
	v_lshlrev_b32_e32 v6, 1, v107
	v_add_u32_e32 v155, s3, v1
	v_add_u32_e32 v156, s52, v1
	v_add_lshl_u32 v1, v18, v9, 1
	v_mov_b32_e32 v63, 0
	v_cmp_eq_u32_e64 s[6:7], 0, v5
	v_mul_u32_u24_e32 v24, 0x90, v5
	v_mul_u32_u24_e32 v25, 0x440, v3
	v_add_u32_e32 v134, s33, v22
	v_add_u32_e32 v135, s34, v22
	v_lshlrev_b32_e32 v22, 2, v9
	v_add3_u32 v144, s0, v143, v6
	v_add3_u32 v154, s0, v153, v6
	v_add_u32_e32 v157, s3, v1
	v_add_u32_e32 v158, s52, v1
	v_add_lshl_u32 v1, v20, v9, 1
	v_lshl_or_b32 v6, v3, 9, v14
	v_lshlrev_b32_e32 v3, 4, v5
	v_and_b32_e32 v5, 7, v178
	v_lshl_add_u64 v[66:67], s[58:59], 0, v[62:63]
	v_mul_u32_u24_e32 v127, 0x90, v107
	v_mad_u32_u24 v129, v107, s42, s42
	v_add_u32_e32 v137, s33, v22
	v_add_u32_e32 v138, s34, v22
	v_lshlrev_b32_e32 v22, 1, v9
	v_add_u32_e32 v159, s3, v1
	v_add_u32_e32 v160, s52, v1
	v_add_lshl_u32 v1, v21, v9, 1
	v_lshlrev_b32_e32 v62, 7, v178
	s_mov_b64 s[0:1], 0x1af02000
	v_lshl_or_b32 v88, v60, 11, v3
	v_mul_u32_u24_e32 v3, 0x5200, v58
	v_lshlrev_b32_e32 v5, 4, v5
	v_add3_u32 v139, s43, v127, v22
	v_add3_u32 v140, s43, v129, v22
	v_add3_u32 v141, s43, v131, v22
	v_add3_u32 v142, s43, v133, v22
	v_add_u32_e32 v161, s3, v1
	v_add_u32_e32 v162, s52, v1
	v_sub_u32_e32 v1, 0x10ff, v178
	v_lshl_add_u64 v[86:87], v[62:63], 0, s[0:1]
	v_mul_hi_u32_u24_e32 v23, 0x5200, v58
	v_or_b32_e32 v22, v3, v5
	s_mov_b64 s[0:1], 0x5348000
	v_or_b32_e32 v12, 1, v12
	v_lshrrev_b32_e32 v84, 9, v1
	v_lshl_add_u64 v[90:91], v[22:23], 0, s[0:1]
	v_lshl_or_b32 v62, v58, 12, v5
	s_mov_b64 s[0:1], 0x1bb40000
	s_mov_b32 s66, 0
	v_mad_u32_u24 v111, v14, s42, v17
	v_lshl_add_u32 v132, v16, 2, s33
	v_mul_u32_u24_e32 v26, 0x110, v12
	v_cmp_le_u32_e64 s[40:41], v9, v16
	s_add_u32 s3, s44, 0x4448000
	v_lshl_add_u32 v68, v12, 7, v14
	v_or_b32_e32 v8, 0x100, v6
	v_or_b32_e32 v10, 0x800, v6
	v_or_b32_e32 v12, 0x900, v6
	v_or_b32_e32 v14, 0x1000, v6
	v_or_b32_e32 v16, 0x1100, v6
	v_or_b32_e32 v18, 0x1800, v6
	v_or_b32_e32 v20, 0x1900, v6
	v_add_u32_e32 v1, 2, v84
	v_lshl_add_u64 v[92:93], v[62:63], 0, s[0:1]
	v_lshlrev_b32_e32 v62, 1, v2
	v_mbcnt_lo_u32_b32 v2, -1, 0
	v_add_u32_e32 v64, 32, v60
	v_cmp_gt_u32_e64 s[4:5], 64, v178
	s_mov_b32 s67, 1
	v_add_u32_e32 v115, 0x120, v113
	v_add_u32_e32 v116, 0x240, v113
	v_add_u32_e32 v117, 0x360, v113
	v_lshl_add_u32 v126, v107, 2, s33
	v_cmp_le_u32_e64 s[34:35], v9, v107
	s_addc_u32 s84, s45, 0
	v_mov_b32_e32 v69, v63
	v_add_u32_e32 v70, 0x180, v6
	v_mov_b32_e32 v71, v63
	v_add_u32_e32 v72, 0x880, v6
	v_mov_b32_e32 v73, v63
	v_add_u32_e32 v74, 0x980, v6
	v_mov_b32_e32 v75, v63
	v_add_u32_e32 v76, 0x1080, v6
	v_mov_b32_e32 v77, v63
	v_add_u32_e32 v78, 0x1180, v6
	v_mov_b32_e32 v79, v63
	v_add_u32_e32 v80, 0x1880, v6
	v_mov_b32_e32 v81, v63
	v_add_u32_e32 v82, 0x1980, v6
	v_mov_b32_e32 v83, v63
	v_and_b32_e32 v163, 30, v1
	v_mov_b32_e32 v1, v84
	v_add_u32_e32 v164, 0x8800, v191
	v_mov_b32_e32 v89, v63
	s_movk_i32 s85, 0x5200
	s_add_i32 s86, 0, 0x20060
	v_lshlrev_b32_e32 v94, 1, v4
	s_add_i32 s87, 0, 0x1a4fc
	v_add_u32_e32 v165, v13, v7
	v_add_u32_e32 v166, v13, v11
	s_movk_i32 s88, 0x7fff
	v_add_u32_e32 v167, v110, v24
	v_add_u32_e32 v168, v15, v25
	v_add_u32_e32 v169, v15, v26
	s_mov_b64 s[68:69], 0x2000
	s_mov_b64 s[70:71], 0x20000
	s_mov_b64 s[72:73], 0x148000
	s_mov_b64 s[74:75], 0x40000
	v_lshlrev_b32_e32 v170, 2, v6
	v_lshlrev_b32_e32 v171, 2, v8
	v_lshlrev_b32_e32 v172, 2, v10
	v_lshlrev_b32_e32 v173, 2, v12
	v_lshlrev_b32_e32 v174, 2, v14
	v_lshlrev_b32_e32 v175, 2, v16
	v_lshlrev_b32_e32 v176, 2, v18
	v_lshlrev_b32_e32 v177, 2, v20
	v_mov_b32_e32 v180, 0x5200
	v_mbcnt_hi_u32_b32 v181, -1, v2
	v_add_u32_e32 v182, v17, v19
	s_mov_b32 s89, s2
	s_mov_b32 s76, s2
	s_branch .LBB0_836

.LBB0_886:
	s_cmpk_gt_i32 s2, 0x1ff
	s_mov_b64 s[84:85], s[96:97]
	s_cbranch_scc1 .LBB0_922
	s_cmp_eq_u32 s98, 2
	s_cbranch_scc1 .LBB0_922
	v_mov_b32_e32 v39, 0
	v_lshlrev_b32_e32 v38, 1, v178
	v_lshl_add_u64 v[4:5], s[46:47], 0, v[38:39]
	s_mov_b64 s[0:1], 0x1bb00000
	v_lshl_add_u64 v[40:41], v[4:5], 0, s[0:1]
	s_movk_i32 s0, 0x100
	v_cmp_gt_u32_e64 s[4:5], s0, v178
	s_movk_i32 s0, 0x80
	v_mov_b32_e32 v4, 0x5000
	v_mov_b32_e32 v5, 0x4000
	v_cmp_gt_u32_e32 vcc, s0, v178
	v_and_b32_e32 v3, 0x7f, v178
	v_and_b32_e32 v34, 7, v178
	s_waitcnt vmcnt(0)
	v_cndmask_b32_e32 v6, v4, v5, vcc
	v_lshlrev_b32_e32 v4, 3, v178
	v_and_b32_e32 v38, 0x400, v4
	v_lshl_add_u64 v[4:5], s[46:47], 0, v[38:39]
	v_lshlrev_b32_e32 v38, 1, v3
	v_lshlrev_b32_e32 v3, 2, v3
	v_add3_u32 v35, 0, v6, v3
	v_lshlrev_b32_e32 v6, 6, v34
	v_lshrrev_b32_e32 v1, 3, v178
	v_lshl_add_u64 v[4:5], v[4:5], 0, v[38:39]
	s_mov_b64 s[0:1], 0x3000000
	v_bfe_u32 v3, v178, 3, 3
	v_add_u32_e32 v87, 0, v6
	v_lshlrev_b32_e32 v36, 9, v1
	v_lshl_add_u64 v[42:43], v[4:5], 0, s[0:1]
	v_lshl_add_u32 v91, v3, 9, v87
	v_lshlrev_b32_e32 v4, 5, v179
	v_lshlrev_b32_e32 v3, 2, v3
	v_lshlrev_b32_e32 v38, 1, v1
	v_add3_u32 v93, 0, v4, v3
	v_lshl_add_u64 v[4:5], s[46:47], 0, v[38:39]
	s_mov_b64 s[0:1], 0x5200000
	v_or_b32_e32 v46, v36, v6
	v_mov_b32_e32 v47, v39
	s_add_u32 s58, s46, 0x1af00000
	v_lshlrev_b32_e32 v3, 5, v34
	v_lshl_add_u64 v[44:45], v[4:5], 0, s[0:1]
	v_lshl_add_u64 v[4:5], s[44:45], 0, v[46:47]
	s_mov_b64 s[0:1], 0x530e020
	v_lshlrev_b32_e32 v2, 4, v34
	s_addc_u32 s59, s47, 0
	v_sub_u32_e32 v95, v87, v3
	v_mul_i32_i24_e32 v3, 0xffffffe4, v34
	v_lshl_add_u64 v[48:49], v[4:5], 0, s[0:1]
	s_add_i32 s0, 0, 0x20018
	v_mov_b32_e32 v37, v39
	s_mov_b32 s43, 0
	v_cmp_gt_u32_e64 s[6:7], 64, v178
	v_cmp_gt_u32_e64 s[8:9], 8, v178
	v_lshl_add_u32 v89, v179, 9, v87
	v_cmp_eq_u32_e64 s[10:11], 0, v34
	v_cmp_ne_u32_e64 s[12:13], 0, v34
	v_lshl_add_u32 v94, v1, 2, 0
	v_cmp_eq_u32_e64 s[14:15], 1, v34
	v_cmp_eq_u32_e64 s[16:17], 2, v34
	v_cmp_eq_u32_e64 s[18:19], 3, v34
	v_cmp_eq_u32_e64 s[20:21], 4, v34
	v_cmp_eq_u32_e64 s[22:23], 5, v34
	v_cmp_eq_u32_e64 s[24:25], 6, v34
	v_cmp_eq_u32_e64 s[26:27], 7, v34
	v_cmp_ne_u32_e64 s[28:29], 7, v34
	v_cmp_lt_u32_e64 s[30:31], 1, v34
	v_cmp_lt_u32_e64 s[34:35], 2, v34
	v_cmp_lt_u32_e64 s[36:37], 3, v34
	v_cmp_lt_u32_e64 s[38:39], 4, v34
	v_cmp_lt_u32_e64 s[40:41], 5, v34
	v_mov_b32_e32 v96, s0
	v_lshlrev_b32_e32 v50, 2, v2
	v_mov_b32_e32 v51, v39
	s_add_i32 s3, 0, 0x20060
	s_add_i32 s82, 0, 0x20068
	s_movk_i32 s83, 0x5200
	s_add_i32 s84, 0, 0x6000
	s_movk_i32 s85, 0x7fff
	v_add_u32_e32 v97, v95, v3
	s_mov_b64 s[60:61], 0x80
	v_lshlrev_b32_e32 v52, 2, v34
	v_add_u32_e32 v98, 0x6000, v191
	s_mov_b32 s86, s2
	s_mov_b32 s87, s2
	s_branch .LBB0_889

.LBB0_922:
	s_cmp_eq_u32 s98, 1
	s_cbranch_scc0 .Lssd_done
	s_mov_b32 s98, 2
	s_branch .Lssd_prompt
